# GLA DMA address block: third-round address arithmetic only on the wave that issues the third DMA
# speedup vs baseline: 1.0014x; 1.0014x over previous
.LBB0_409:
	s_lshl_b32 s2, s25, 6
	s_add_u32 s77, s15, s2
	s_addc_u32 s25, s14, 0
	v_mov_b64_e32 v[34:35], s[88:89]
	s_mul_i32 vcc_lo, s25, 0x1c00
	s_mov_b32 s25, s9
	s_mov_b32 s85, s9
	v_or_b32_e32 v36, s77, v184
	v_mad_u64_u32 v[36:37], s[2:3], v36, s13, v[34:35]
	v_add_u32_e32 v37, vcc_lo, v37
	v_lshl_add_u64 v[70:71], v[36:37], 0, s[8:9]
	v_lshl_add_u64 v[76:77], v[36:37], 0, s[24:25]
	v_lshl_add_u64 v[76:77], v[76:77], 0, s[84:85]
	v_lshl_add_u64 v[70:71], v[70:71], 0, v[200:201]
	v_lshl_add_u64 v[76:77], v[76:77], 0, v[192:193]
	v_or_b32_e32 v36, s77, v185
	v_mad_u64_u32 v[36:37], s[2:3], v36, s13, v[34:35]
	v_add_u32_e32 v37, vcc_lo, v37
	v_lshl_add_u64 v[72:73], v[36:37], 0, s[8:9]
	v_lshl_add_u64 v[78:79], v[36:37], 0, s[24:25]
	v_lshl_add_u64 v[78:79], v[78:79], 0, s[84:85]
	v_lshl_add_u64 v[72:73], v[72:73], 0, v[248:249]
	v_lshl_add_u64 v[78:79], v[78:79], 0, v[194:195]
	s_cmp_lg_u32 s18, 0
	s_cbranch_scc1 .Lg8_nr2
	v_or_b32_e32 v36, s77, v205
	v_mad_u64_u32 v[36:37], s[2:3], v36, s13, v[34:35]
	v_add_u32_e32 v37, vcc_lo, v37
	v_lshl_add_u64 v[74:75], v[36:37], 0, s[8:9]
	v_lshl_add_u64 v[80:81], v[36:37], 0, s[24:25]
	v_lshl_add_u64 v[80:81], v[80:81], 0, s[84:85]
	v_lshl_add_u64 v[74:75], v[74:75], 0, v[250:251]
	v_lshl_add_u64 v[80:81], v[80:81], 0, v[196:197]
